# v038: v036 + register-cached rstd (S) values in F32 fused-norm epilogue: 8 LDS preloads replace 32 serialized re-reads in x_new and final sections
# baseline (speedup 1.0000x reference)
; __device__ __forceinline__ float f16lo(unsigned w) { return (float)__builtin_bit_cast(f16x2, w)[0]; }
; __device__ __forceinline__ float f16hi(unsigned w) { return (float)__builtin_bit_cast(f16x2, w)[1]; }
;     __device__ __forceinline__ void fused(f32x4 (&acc)[2][2][4][2], const Unit& u, int wr, int wc, int fr, int fq, PG8_LAS unsigned char* lds, int wid, int lane) const {
;     ...
;         for (int bj = 0; bj < 2; ++bj)
; #pragma unroll
;             for (int n = 0; n < 2; ++n) {
;                 const int c = col0 + bj * HALF + n * 4;
;                 const f32x4 gg = *(const f32x4*)(gate + (size_t)b * 9216 + c) * *(const f32x4*)(gpost + c) * res_w;
; #pragma unroll
;                 for (int ai = 0; ai < 2; ++ai)
; #pragma unroll
;                     for (int m = 0; m < 4; ++m) { const int r = ai * HALF + wr * 64 + m * 16 + fr;
;                         const unsigned w0 = n ? pre[ai][m][bj].z : pre[ai][m][bj].x, w1 = n ? pre[ai][m][bj].w : pre[ai][m][bj].y;
;                         const f32x4 xv = {f16lo(w0), f16hi(w0), f16lo(w1), f16hi(w1)};
;                         acc[ai][bj][m][n] = xv + gg * (acc[ai][bj][m][n] * S[r]); }
;                 asm volatile("" ::: "memory");
;             }
.LBB0_753:
	s_or_b64 exec, exec, s[34:35]
	s_ashr_i32 s8, s39, 31
	s_lshr_b32 s8, s8, 27
	s_add_i32 s8, s39, s8
	s_ashr_i32 s8, s8, 5
	s_mul_i32 s35, s8, 0x9000
	s_mul_hi_i32 s34, s8, 0x9000
	s_add_u32 s8, s30, s35
	s_addc_u32 s9, s31, s34
	s_waitcnt lgkmcnt(0)
	v_lshlrev_b64 v[208:209], 2, v[0:1]
	s_waitcnt lgkmcnt(0)
	s_barrier
	v_lshl_add_u64 v[210:211], s[8:9], 0, v[208:209]
	v_lshl_add_u64 v[212:213], s[28:29], 0, v[208:209]
	flat_load_dwordx4 v[214:217], v[210:211]
	flat_load_dwordx4 v[236:239], v[212:213]
	s_and_b32 s11, s17, 0xffffff00
	s_add_i32 s11, s11, 0
	v_lshl_add_u32 v227, v219, 2, s11
	s_cmp_lg_u64 s[12:13], 0
	s_cselect_b64 s[8:9], -1, 0
	s_cmp_eq_u64 s[12:13], 0
	s_waitcnt vmcnt(0) lgkmcnt(0)
	v_pk_mul_f32 v[216:217], v[216:217], v[238:239]
	v_pk_mul_f32 v[236:237], v[214:215], v[236:237]
	v_pk_mul_f32 v[214:215], s[16:17], v[216:217] op_sel_hi:[0,1]
	v_pk_mul_f32 v[216:217], s[16:17], v[236:237] op_sel_hi:[0,1]
	v_cvt_f32_f16_sdwa v237, v192 dst_sel:DWORD dst_unused:UNUSED_PAD src0_sel:WORD_1
	v_cvt_f32_f16_e32 v236, v192
	v_add_u32_e32 v192, 0x1000, v227
	ds_read2_b32 v[244:245], v192 offset1:16
	ds_read2_b32 v[246:247], v192 offset0:32 offset1:48
	ds_read2_b32 v[248:249], v192 offset0:128 offset1:144
	ds_read2_b32 v[250:251], v192 offset0:160 offset1:176
	s_waitcnt lgkmcnt(0)
	v_mov_b32_e32 v240, v244
	v_mov_b32_e32 v241, v245
	v_cvt_f32_f16_sdwa v239, v193 dst_sel:DWORD dst_unused:UNUSED_PAD src0_sel:WORD_1
	v_cvt_f32_f16_e32 v238, v193
	s_waitcnt lgkmcnt(0)
	v_pk_mul_f32 v[96:97], v[96:97], v[240:241] op_sel_hi:[1,0]
	s_nop 0
	v_pk_fma_f32 v[96:97], v[216:217], v[96:97], v[236:237]
	v_cvt_f32_f16_sdwa v237, v188 dst_sel:DWORD dst_unused:UNUSED_PAD src0_sel:WORD_1
	v_cvt_f32_f16_e32 v236, v188
	v_mov_b32_e32 v188, v241
	v_pk_mul_f32 v[98:99], v[98:99], v[240:241] op_sel_hi:[1,0]
	v_pk_mul_f32 v[88:89], v[88:89], v[188:189] op_sel_hi:[1,0]
	v_pk_fma_f32 v[98:99], v[214:215], v[98:99], v[238:239]
	v_cvt_f32_f16_sdwa v239, v189 dst_sel:DWORD dst_unused:UNUSED_PAD src0_sel:WORD_1
	v_cvt_f32_f16_e32 v238, v189
	v_pk_mul_f32 v[90:91], v[90:91], v[188:189] op_sel_hi:[1,0]
	v_pk_fma_f32 v[88:89], v[216:217], v[88:89], v[236:237]
	v_cvt_f32_f16_sdwa v189, v184 dst_sel:DWORD dst_unused:UNUSED_PAD src0_sel:WORD_1
	v_cvt_f32_f16_e32 v188, v184
	v_cvt_f32_f16_sdwa v237, v185 dst_sel:DWORD dst_unused:UNUSED_PAD src0_sel:WORD_1
	v_cvt_f32_f16_e32 v236, v185
	s_waitcnt lgkmcnt(0)
	v_mov_b32_e32 v184, v246
	v_mov_b32_e32 v185, v247
	v_pk_fma_f32 v[90:91], v[214:215], v[90:91], v[238:239]
	s_waitcnt lgkmcnt(0)
	v_pk_mul_f32 v[92:93], v[92:93], v[184:185] op_sel_hi:[1,0]
	v_pk_mul_f32 v[94:95], v[94:95], v[184:185] op_sel_hi:[1,0]
	v_pk_fma_f32 v[92:93], v[216:217], v[92:93], v[188:189]
	v_cvt_f32_f16_sdwa v189, v180 dst_sel:DWORD dst_unused:UNUSED_PAD src0_sel:WORD_1
	v_cvt_f32_f16_e32 v188, v180
	v_mov_b32_e32 v180, v185
	v_pk_fma_f32 v[94:95], v[214:215], v[94:95], v[236:237]
	v_cvt_f32_f16_sdwa v237, v181 dst_sel:DWORD dst_unused:UNUSED_PAD src0_sel:WORD_1
	v_cvt_f32_f16_e32 v236, v181
	v_pk_mul_f32 v[74:75], v[74:75], v[180:181] op_sel_hi:[1,0]
	v_pk_mul_f32 v[72:73], v[72:73], v[180:181] op_sel_hi:[1,0]
	v_cvt_f32_f16_sdwa v181, v176 dst_sel:DWORD dst_unused:UNUSED_PAD src0_sel:WORD_1
	v_cvt_f32_f16_e32 v180, v176
	v_cvt_f32_f16_sdwa v185, v177 dst_sel:DWORD dst_unused:UNUSED_PAD src0_sel:WORD_1
	v_cvt_f32_f16_e32 v184, v177
	s_waitcnt lgkmcnt(0)
	v_mov_b32_e32 v176, v248
	v_mov_b32_e32 v177, v249
	v_pk_fma_f32 v[74:75], v[214:215], v[74:75], v[236:237]
	v_pk_fma_f32 v[72:73], v[216:217], v[72:73], v[188:189]
	s_waitcnt lgkmcnt(0)
	v_pk_mul_f32 v[80:81], v[80:81], v[176:177] op_sel_hi:[1,0]
	v_pk_mul_f32 v[82:83], v[82:83], v[176:177] op_sel_hi:[1,0]
	v_pk_fma_f32 v[80:81], v[216:217], v[80:81], v[180:181]
	v_cvt_f32_f16_sdwa v181, v172 dst_sel:DWORD dst_unused:UNUSED_PAD src0_sel:WORD_1
	v_cvt_f32_f16_e32 v180, v172
	v_mov_b32_e32 v172, v177
	v_pk_fma_f32 v[82:83], v[214:215], v[82:83], v[184:185]
	v_cvt_f32_f16_sdwa v185, v173 dst_sel:DWORD dst_unused:UNUSED_PAD src0_sel:WORD_1
	v_cvt_f32_f16_e32 v184, v173
	v_pk_mul_f32 v[66:67], v[66:67], v[172:173] op_sel_hi:[1,0]
	v_pk_mul_f32 v[64:65], v[64:65], v[172:173] op_sel_hi:[1,0]
	v_cvt_f32_f16_sdwa v173, v168 dst_sel:DWORD dst_unused:UNUSED_PAD src0_sel:WORD_1
	v_cvt_f32_f16_e32 v172, v168
	v_cvt_f32_f16_sdwa v177, v169 dst_sel:DWORD dst_unused:UNUSED_PAD src0_sel:WORD_1
	v_cvt_f32_f16_e32 v176, v169
	s_waitcnt lgkmcnt(0)
	v_mov_b32_e32 v168, v250
	v_mov_b32_e32 v169, v251
	v_pk_fma_f32 v[66:67], v[214:215], v[66:67], v[184:185]
	v_pk_fma_f32 v[64:65], v[216:217], v[64:65], v[180:181]
	s_waitcnt lgkmcnt(0)
	v_pk_mul_f32 v[70:71], v[70:71], v[168:169] op_sel_hi:[1,0]
	v_pk_mul_f32 v[68:69], v[68:69], v[168:169] op_sel_hi:[1,0]
	v_pk_fma_f32 v[70:71], v[214:215], v[70:71], v[176:177]
	v_pk_fma_f32 v[68:69], v[216:217], v[68:69], v[172:173]
	v_cvt_f32_f16_sdwa v173, v164 dst_sel:DWORD dst_unused:UNUSED_PAD src0_sel:WORD_1
	v_cvt_f32_f16_e32 v172, v164
	v_cvt_f32_f16_sdwa v177, v165 dst_sel:DWORD dst_unused:UNUSED_PAD src0_sel:WORD_1
	v_cvt_f32_f16_e32 v176, v165
	v_mov_b32_e32 v164, v169
	v_pk_mul_f32 v[54:55], v[54:55], v[164:165] op_sel_hi:[1,0]
	v_pk_mul_f32 v[52:53], v[52:53], v[164:165] op_sel_hi:[1,0]
	v_pk_fma_f32 v[54:55], v[214:215], v[54:55], v[176:177]
	v_pk_fma_f32 v[52:53], v[216:217], v[52:53], v[172:173]
	flat_load_dwordx4 v[214:217], v[210:211] offset:16
	flat_load_dwordx4 v[236:239], v[212:213] offset:16
	s_waitcnt lgkmcnt(0)
; __device__ __forceinline__ float f16lo(unsigned w) { return (float)__builtin_bit_cast(f16x2, w)[0]; }
; __device__ __forceinline__ float f16hi(unsigned w) { return (float)__builtin_bit_cast(f16x2, w)[1]; }
;     __device__ __forceinline__ void fused(f32x4 (&acc)[2][2][4][2], const Unit& u, int wr, int wc, int fr, int fq, PG8_LAS unsigned char* lds, int wid, int lane) const {
;     ...
;         for (int bj = 0; bj < 2; ++bj)
; #pragma unroll
;             for (int n = 0; n < 2; ++n) {
;                 const int c = col0 + bj * HALF + n * 4;
;                 const f32x4 gg = *(const f32x4*)(gate + (size_t)b * 9216 + c) * *(const f32x4*)(gpost + c) * res_w;
; #pragma unroll
;                 for (int ai = 0; ai < 2; ++ai)
; #pragma unroll
;                     for (int m = 0; m < 4; ++m) { const int r = ai * HALF + wr * 64 + m * 16 + fr;
;                         const unsigned w0 = n ? pre[ai][m][bj].z : pre[ai][m][bj].x, w1 = n ? pre[ai][m][bj].w : pre[ai][m][bj].y;
;                         const f32x4 xv = {f16lo(w0), f16hi(w0), f16lo(w1), f16hi(w1)};
;                         acc[ai][bj][m][n] = xv + gg * (acc[ai][bj][m][n] * S[r]); }
;                 asm volatile("" ::: "memory");
;             }
	v_mov_b32_e32 v180, v244
	v_mov_b32_e32 v181, v245
	v_cvt_f32_f16_sdwa v173, v194 dst_sel:DWORD dst_unused:UNUSED_PAD src0_sel:WORD_1
	v_cvt_f32_f16_e32 v172, v194
	v_cvt_f32_f16_sdwa v177, v195 dst_sel:DWORD dst_unused:UNUSED_PAD src0_sel:WORD_1
	v_cvt_f32_f16_e32 v176, v195
	s_waitcnt lgkmcnt(0)
	v_pk_mul_f32 v[162:163], v[162:163], v[180:181] op_sel_hi:[1,0]
	v_pk_mul_f32 v[160:161], v[160:161], v[180:181] op_sel_hi:[1,0]
	v_mov_b32_e32 v180, v181
	v_pk_mul_f32 v[158:159], v[158:159], v[180:181] op_sel_hi:[1,0]
	v_pk_mul_f32 v[156:157], v[156:157], v[180:181] op_sel_hi:[1,0]
	s_waitcnt lgkmcnt(0)
	v_mov_b32_e32 v180, v246
	v_mov_b32_e32 v181, v247
	s_waitcnt lgkmcnt(0)
	v_pk_mul_f32 v[154:155], v[154:155], v[180:181] op_sel_hi:[1,0]
	v_pk_mul_f32 v[152:153], v[152:153], v[180:181] op_sel_hi:[1,0]
	v_mov_b32_e32 v180, v181
	v_pk_mul_f32 v[150:151], v[150:151], v[180:181] op_sel_hi:[1,0]
	v_pk_mul_f32 v[148:149], v[148:149], v[180:181] op_sel_hi:[1,0]
	s_waitcnt vmcnt(0)
	v_pk_mul_f32 v[164:165], v[216:217], v[238:239]
	v_pk_mul_f32 v[168:169], v[214:215], v[236:237]
	v_pk_mul_f32 v[164:165], s[16:17], v[164:165] op_sel_hi:[0,1]
	v_pk_mul_f32 v[168:169], s[16:17], v[168:169] op_sel_hi:[0,1]
	v_pk_fma_f32 v[162:163], v[164:165], v[162:163], v[176:177]
	v_pk_fma_f32 v[160:161], v[168:169], v[160:161], v[172:173]
	v_cvt_f32_f16_sdwa v173, v190 dst_sel:DWORD dst_unused:UNUSED_PAD src0_sel:WORD_1
	v_cvt_f32_f16_e32 v172, v190
	v_cvt_f32_f16_sdwa v177, v191 dst_sel:DWORD dst_unused:UNUSED_PAD src0_sel:WORD_1
	v_cvt_f32_f16_e32 v176, v191
	v_pk_fma_f32 v[156:157], v[168:169], v[156:157], v[172:173]
	v_cvt_f32_f16_sdwa v173, v186 dst_sel:DWORD dst_unused:UNUSED_PAD src0_sel:WORD_1
	v_pk_fma_f32 v[158:159], v[164:165], v[158:159], v[176:177]
	v_cvt_f32_f16_e32 v172, v186
	v_cvt_f32_f16_sdwa v177, v187 dst_sel:DWORD dst_unused:UNUSED_PAD src0_sel:WORD_1
	v_cvt_f32_f16_e32 v176, v187
	v_pk_fma_f32 v[152:153], v[168:169], v[152:153], v[172:173]
	v_cvt_f32_f16_sdwa v173, v182 dst_sel:DWORD dst_unused:UNUSED_PAD src0_sel:WORD_1
	v_pk_fma_f32 v[154:155], v[164:165], v[154:155], v[176:177]
	v_cvt_f32_f16_e32 v172, v182
	v_cvt_f32_f16_sdwa v177, v183 dst_sel:DWORD dst_unused:UNUSED_PAD src0_sel:WORD_1
	v_cvt_f32_f16_e32 v176, v183
	v_pk_fma_f32 v[148:149], v[168:169], v[148:149], v[172:173]
	v_cvt_f32_f16_sdwa v173, v178 dst_sel:DWORD dst_unused:UNUSED_PAD src0_sel:WORD_1
	v_pk_fma_f32 v[150:151], v[164:165], v[150:151], v[176:177]
	v_cvt_f32_f16_e32 v172, v178
	v_cvt_f32_f16_sdwa v177, v179 dst_sel:DWORD dst_unused:UNUSED_PAD src0_sel:WORD_1
	v_cvt_f32_f16_e32 v176, v179
	s_waitcnt lgkmcnt(0)
	v_mov_b32_e32 v178, v248
	v_mov_b32_e32 v179, v249
	s_waitcnt lgkmcnt(0)
	v_pk_mul_f32 v[144:145], v[144:145], v[178:179] op_sel_hi:[1,0]
	s_nop 0
	v_pk_fma_f32 v[144:145], v[168:169], v[144:145], v[172:173]
	v_cvt_f32_f16_sdwa v173, v174 dst_sel:DWORD dst_unused:UNUSED_PAD src0_sel:WORD_1
	v_cvt_f32_f16_e32 v172, v174
	v_mov_b32_e32 v174, v179
	v_pk_mul_f32 v[146:147], v[146:147], v[178:179] op_sel_hi:[1,0]
	v_pk_mul_f32 v[136:137], v[136:137], v[174:175] op_sel_hi:[1,0]
	v_pk_fma_f32 v[146:147], v[164:165], v[146:147], v[176:177]
	v_cvt_f32_f16_sdwa v177, v175 dst_sel:DWORD dst_unused:UNUSED_PAD src0_sel:WORD_1
	v_cvt_f32_f16_e32 v176, v175
	v_pk_mul_f32 v[138:139], v[138:139], v[174:175] op_sel_hi:[1,0]
	v_pk_fma_f32 v[136:137], v[168:169], v[136:137], v[172:173]
	v_cvt_f32_f16_sdwa v173, v170 dst_sel:DWORD dst_unused:UNUSED_PAD src0_sel:WORD_1
	v_cvt_f32_f16_e32 v172, v170
	v_cvt_f32_f16_sdwa v175, v171 dst_sel:DWORD dst_unused:UNUSED_PAD src0_sel:WORD_1
	v_cvt_f32_f16_e32 v174, v171
	s_waitcnt lgkmcnt(0)
	v_mov_b32_e32 v170, v250
	v_mov_b32_e32 v171, v251
	v_pk_fma_f32 v[138:139], v[164:165], v[138:139], v[176:177]
	s_waitcnt lgkmcnt(0)
	v_pk_mul_f32 v[118:119], v[118:119], v[170:171] op_sel_hi:[1,0]
	v_pk_mul_f32 v[116:117], v[116:117], v[170:171] op_sel_hi:[1,0]
	v_pk_fma_f32 v[118:119], v[164:165], v[118:119], v[174:175]
	v_pk_fma_f32 v[116:117], v[168:169], v[116:117], v[172:173]
	v_cvt_f32_f16_sdwa v173, v166 dst_sel:DWORD dst_unused:UNUSED_PAD src0_sel:WORD_1
	v_cvt_f32_f16_e32 v172, v166
	v_cvt_f32_f16_sdwa v175, v167 dst_sel:DWORD dst_unused:UNUSED_PAD src0_sel:WORD_1
	v_cvt_f32_f16_e32 v174, v167
	v_mov_b32_e32 v166, v171
	v_pk_mul_f32 v[114:115], v[114:115], v[166:167] op_sel_hi:[1,0]
	v_pk_mul_f32 v[112:113], v[112:113], v[166:167] op_sel_hi:[1,0]
	v_pk_fma_f32 v[114:115], v[164:165], v[114:115], v[174:175]
	v_pk_fma_f32 v[112:113], v[168:169], v[112:113], v[172:173]
	flat_load_dwordx4 v[164:167], v[210:211] offset:512
	flat_load_dwordx4 v[168:171], v[212:213] offset:512
	s_waitcnt vmcnt(0) lgkmcnt(0)
	v_pk_mul_f32 v[166:167], v[166:167], v[170:171]
	v_pk_mul_f32 v[168:169], v[164:165], v[168:169]
	v_pk_mul_f32 v[164:165], s[16:17], v[166:167] op_sel_hi:[0,1]
	v_pk_mul_f32 v[166:167], s[16:17], v[168:169] op_sel_hi:[0,1]
	v_cvt_f32_f16_sdwa v169, v140 dst_sel:DWORD dst_unused:UNUSED_PAD src0_sel:WORD_1
	v_cvt_f32_f16_e32 v168, v140
	v_cvt_f32_f16_sdwa v171, v141 dst_sel:DWORD dst_unused:UNUSED_PAD src0_sel:WORD_1
	v_cvt_f32_f16_e32 v170, v141
	s_waitcnt lgkmcnt(0)
	v_mov_b32_e32 v140, v244
	v_mov_b32_e32 v141, v245
	s_waitcnt lgkmcnt(0)
; __device__ __forceinline__ float f16lo(unsigned w) { return (float)__builtin_bit_cast(f16x2, w)[0]; }
; __device__ __forceinline__ float f16hi(unsigned w) { return (float)__builtin_bit_cast(f16x2, w)[1]; }
;     __device__ __forceinline__ void fused(f32x4 (&acc)[2][2][4][2], const Unit& u, int wr, int wc, int fr, int fq, PG8_LAS unsigned char* lds, int wid, int lane) const {
;     ...
;         for (int bj = 0; bj < 2; ++bj)
; #pragma unroll
;             for (int n = 0; n < 2; ++n) {
;                 const int c = col0 + bj * HALF + n * 4;
;                 const f32x4 gg = *(const f32x4*)(gate + (size_t)b * 9216 + c) * *(const f32x4*)(gpost + c) * res_w;
; #pragma unroll
;                 for (int ai = 0; ai < 2; ++ai)
; #pragma unroll
;                     for (int m = 0; m < 4; ++m) { const int r = ai * HALF + wr * 64 + m * 16 + fr;
;                         const unsigned w0 = n ? pre[ai][m][bj].z : pre[ai][m][bj].x, w1 = n ? pre[ai][m][bj].w : pre[ai][m][bj].y;
;                         const f32x4 xv = {f16lo(w0), f16hi(w0), f16lo(w1), f16hi(w1)};
;                         acc[ai][bj][m][n] = xv + gg * (acc[ai][bj][m][n] * S[r]); }
;                 asm volatile("" ::: "memory");
;             }
	v_pk_mul_f32 v[84:85], v[84:85], v[140:141] op_sel_hi:[1,0]
	v_pk_mul_f32 v[86:87], v[86:87], v[140:141] op_sel_hi:[1,0]
	v_pk_fma_f32 v[84:85], v[166:167], v[84:85], v[168:169]
	v_cvt_f32_f16_sdwa v169, v132 dst_sel:DWORD dst_unused:UNUSED_PAD src0_sel:WORD_1
	v_cvt_f32_f16_e32 v168, v132
	v_mov_b32_e32 v132, v141
	v_pk_fma_f32 v[86:87], v[164:165], v[86:87], v[170:171]
	v_cvt_f32_f16_sdwa v171, v133 dst_sel:DWORD dst_unused:UNUSED_PAD src0_sel:WORD_1
	v_cvt_f32_f16_e32 v170, v133
	v_pk_mul_f32 v[78:79], v[78:79], v[132:133] op_sel_hi:[1,0]
	v_pk_mul_f32 v[76:77], v[76:77], v[132:133] op_sel_hi:[1,0]
	v_cvt_f32_f16_sdwa v133, v128 dst_sel:DWORD dst_unused:UNUSED_PAD src0_sel:WORD_1
	v_cvt_f32_f16_e32 v132, v128
	v_cvt_f32_f16_sdwa v141, v129 dst_sel:DWORD dst_unused:UNUSED_PAD src0_sel:WORD_1
	v_cvt_f32_f16_e32 v140, v129
	s_waitcnt lgkmcnt(0)
	v_mov_b32_e32 v128, v246
	v_mov_b32_e32 v129, v247
	v_pk_fma_f32 v[78:79], v[164:165], v[78:79], v[170:171]
	v_pk_fma_f32 v[76:77], v[166:167], v[76:77], v[168:169]
	s_waitcnt lgkmcnt(0)
	v_pk_mul_f32 v[60:61], v[60:61], v[128:129] op_sel_hi:[1,0]
	v_pk_mul_f32 v[62:63], v[62:63], v[128:129] op_sel_hi:[1,0]
	v_pk_fma_f32 v[60:61], v[166:167], v[60:61], v[132:133]
	v_cvt_f32_f16_sdwa v133, v124 dst_sel:DWORD dst_unused:UNUSED_PAD src0_sel:WORD_1
	v_cvt_f32_f16_e32 v132, v124
	v_mov_b32_e32 v124, v129
	v_pk_fma_f32 v[62:63], v[164:165], v[62:63], v[140:141]
	v_cvt_f32_f16_sdwa v141, v125 dst_sel:DWORD dst_unused:UNUSED_PAD src0_sel:WORD_1
	v_cvt_f32_f16_e32 v140, v125
	v_pk_mul_f32 v[58:59], v[58:59], v[124:125] op_sel_hi:[1,0]
	v_pk_mul_f32 v[56:57], v[56:57], v[124:125] op_sel_hi:[1,0]
	v_cvt_f32_f16_sdwa v125, v120 dst_sel:DWORD dst_unused:UNUSED_PAD src0_sel:WORD_1
	v_cvt_f32_f16_e32 v124, v120
	v_cvt_f32_f16_sdwa v129, v121 dst_sel:DWORD dst_unused:UNUSED_PAD src0_sel:WORD_1
	v_cvt_f32_f16_e32 v128, v121
	s_waitcnt lgkmcnt(0)
	v_mov_b32_e32 v120, v248
	v_mov_b32_e32 v121, v249
	v_pk_fma_f32 v[58:59], v[164:165], v[58:59], v[140:141]
	v_pk_fma_f32 v[56:57], v[166:167], v[56:57], v[132:133]
	s_waitcnt lgkmcnt(0)
	v_pk_mul_f32 v[48:49], v[48:49], v[120:121] op_sel_hi:[1,0]
	v_pk_mul_f32 v[50:51], v[50:51], v[120:121] op_sel_hi:[1,0]
	v_pk_fma_f32 v[48:49], v[166:167], v[48:49], v[124:125]
	v_cvt_f32_f16_sdwa v125, v108 dst_sel:DWORD dst_unused:UNUSED_PAD src0_sel:WORD_1
	v_cvt_f32_f16_e32 v124, v108
	v_mov_b32_e32 v108, v121
	v_pk_fma_f32 v[50:51], v[164:165], v[50:51], v[128:129]
	v_cvt_f32_f16_sdwa v129, v109 dst_sel:DWORD dst_unused:UNUSED_PAD src0_sel:WORD_1
	v_cvt_f32_f16_e32 v128, v109
	v_pk_mul_f32 v[46:47], v[46:47], v[108:109] op_sel_hi:[1,0]
	v_pk_mul_f32 v[44:45], v[44:45], v[108:109] op_sel_hi:[1,0]
	v_cvt_f32_f16_sdwa v109, v104 dst_sel:DWORD dst_unused:UNUSED_PAD src0_sel:WORD_1
	v_cvt_f32_f16_e32 v108, v104
	v_cvt_f32_f16_sdwa v121, v105 dst_sel:DWORD dst_unused:UNUSED_PAD src0_sel:WORD_1
	v_cvt_f32_f16_e32 v120, v105
	s_waitcnt lgkmcnt(0)
	v_mov_b32_e32 v104, v250
	v_mov_b32_e32 v105, v251
	v_pk_fma_f32 v[46:47], v[164:165], v[46:47], v[128:129]
	v_pk_fma_f32 v[44:45], v[166:167], v[44:45], v[124:125]
	s_waitcnt lgkmcnt(0)
	v_pk_mul_f32 v[42:43], v[42:43], v[104:105] op_sel_hi:[1,0]
	v_pk_mul_f32 v[40:41], v[40:41], v[104:105] op_sel_hi:[1,0]
	v_pk_fma_f32 v[42:43], v[164:165], v[42:43], v[120:121]
	v_pk_fma_f32 v[40:41], v[166:167], v[40:41], v[108:109]
	v_cvt_f32_f16_sdwa v109, v100 dst_sel:DWORD dst_unused:UNUSED_PAD src0_sel:WORD_1
	v_cvt_f32_f16_e32 v108, v100
	v_cvt_f32_f16_sdwa v121, v101 dst_sel:DWORD dst_unused:UNUSED_PAD src0_sel:WORD_1
	v_cvt_f32_f16_e32 v120, v101
	v_mov_b32_e32 v100, v105
	v_pk_mul_f32 v[38:39], v[38:39], v[100:101] op_sel_hi:[1,0]
	v_pk_mul_f32 v[36:37], v[36:37], v[100:101] op_sel_hi:[1,0]
	v_pk_fma_f32 v[38:39], v[164:165], v[38:39], v[120:121]
	v_pk_fma_f32 v[36:37], v[166:167], v[36:37], v[108:109]
	flat_load_dwordx4 v[164:167], v[210:211] offset:528
	flat_load_dwordx4 v[168:171], v[212:213] offset:528
	s_waitcnt lgkmcnt(0)
	v_mov_b32_e32 v124, v244
	v_mov_b32_e32 v125, v245
	v_cvt_f32_f16_sdwa v109, v142 dst_sel:DWORD dst_unused:UNUSED_PAD src0_sel:WORD_1
	v_cvt_f32_f16_e32 v108, v142
	v_cvt_f32_f16_sdwa v121, v143 dst_sel:DWORD dst_unused:UNUSED_PAD src0_sel:WORD_1
	v_cvt_f32_f16_e32 v120, v143
	s_waitcnt lgkmcnt(0)
	v_pk_mul_f32 v[34:35], v[34:35], v[124:125] op_sel_hi:[1,0]
	v_pk_mul_f32 v[32:33], v[32:33], v[124:125] op_sel_hi:[1,0]
	v_mov_b32_e32 v124, v125
	v_pk_mul_f32 v[30:31], v[30:31], v[124:125] op_sel_hi:[1,0]
	v_pk_mul_f32 v[28:29], v[28:29], v[124:125] op_sel_hi:[1,0]
	s_waitcnt lgkmcnt(0)
	v_mov_b32_e32 v124, v246
	v_mov_b32_e32 v125, v247
	s_waitcnt lgkmcnt(0)
; __device__ __forceinline__ float f16lo(unsigned w) { return (float)__builtin_bit_cast(f16x2, w)[0]; }
; __device__ __forceinline__ float f16hi(unsigned w) { return (float)__builtin_bit_cast(f16x2, w)[1]; }
; __device__ __forceinline__ void panel_rstd(const f32x4 (&v)[2][2][4][2], const Unit& u, int wr, int wc, int fr, int fq, PG8_LAS unsigned char* lds, int wid, int lane,
;                                            float* xslots, unsigned* cnt, unsigned want, float eps) {
;     ...
; #pragma unroll
;     for (int ai = 0; ai < 2; ++ai)
; #pragma unroll
;         for (int m = 0; m < 4; ++m) {
;             float s = 0.f;
; #pragma unroll
;             for (int bj = 0; bj < 2; ++bj)
; #pragma unroll
;                 for (int n = 0; n < 2; ++n) { const f32x4 x = v[ai][bj][m][n]; s += (x[0] * x[0] + x[1] * x[1]) + (x[2] * x[2] + x[3] * x[3]); }
;             s += __shfl_xor(s, 16); s += __shfl_xor(s, 32);
;             if (fq == 0) P[(ai * HALF + wr * 64 + m * 16 + fr) * 4 + wc] = s;
;     __device__ __forceinline__ void fused(f32x4 (&acc)[2][2][4][2], const Unit& u, int wr, int wc, int fr, int fq, PG8_LAS unsigned char* lds, int wid, int lane) const {
;     ...
;         for (int bj = 0; bj < 2; ++bj)
; #pragma unroll
;             for (int n = 0; n < 2; ++n) {
;                 const int c = col0 + bj * HALF + n * 4;
;                 const f32x4 gg = *(const f32x4*)(gate + (size_t)b * 9216 + c) * *(const f32x4*)(gpost + c) * res_w;
; #pragma unroll
;                 for (int ai = 0; ai < 2; ++ai)
; #pragma unroll
;                     for (int m = 0; m < 4; ++m) { const int r = ai * HALF + wr * 64 + m * 16 + fr;
;                         const unsigned w0 = n ? pre[ai][m][bj].z : pre[ai][m][bj].x, w1 = n ? pre[ai][m][bj].w : pre[ai][m][bj].y;
;                         const f32x4 xv = {f16lo(w0), f16hi(w0), f16lo(w1), f16hi(w1)};
;                         acc[ai][bj][m][n] = xv + gg * (acc[ai][bj][m][n] * S[r]); }
;                 asm volatile("" ::: "memory");
;             }
	v_pk_mul_f32 v[26:27], v[26:27], v[124:125] op_sel_hi:[1,0]
	v_pk_mul_f32 v[24:25], v[24:25], v[124:125] op_sel_hi:[1,0]
	v_mov_b32_e32 v124, v125
	v_pk_mul_f32 v[22:23], v[22:23], v[124:125] op_sel_hi:[1,0]
	v_pk_mul_f32 v[20:21], v[20:21], v[124:125] op_sel_hi:[1,0]
	s_waitcnt vmcnt(0)
	v_pk_mul_f32 v[100:101], v[166:167], v[170:171]
	v_pk_mul_f32 v[104:105], v[164:165], v[168:169]
	v_pk_mul_f32 v[100:101], s[16:17], v[100:101] op_sel_hi:[0,1]
	v_pk_mul_f32 v[104:105], s[16:17], v[104:105] op_sel_hi:[0,1]
	v_pk_fma_f32 v[34:35], v[100:101], v[34:35], v[120:121]
	v_pk_fma_f32 v[32:33], v[104:105], v[32:33], v[108:109]
	v_cvt_f32_f16_sdwa v109, v134 dst_sel:DWORD dst_unused:UNUSED_PAD src0_sel:WORD_1
	v_cvt_f32_f16_e32 v108, v134
	v_cvt_f32_f16_sdwa v121, v135 dst_sel:DWORD dst_unused:UNUSED_PAD src0_sel:WORD_1
	v_cvt_f32_f16_e32 v120, v135
	v_pk_fma_f32 v[28:29], v[104:105], v[28:29], v[108:109]
	v_cvt_f32_f16_sdwa v109, v130 dst_sel:DWORD dst_unused:UNUSED_PAD src0_sel:WORD_1
	v_pk_fma_f32 v[30:31], v[100:101], v[30:31], v[120:121]
	v_cvt_f32_f16_e32 v108, v130
	v_cvt_f32_f16_sdwa v121, v131 dst_sel:DWORD dst_unused:UNUSED_PAD src0_sel:WORD_1
	v_cvt_f32_f16_e32 v120, v131
	v_pk_fma_f32 v[24:25], v[104:105], v[24:25], v[108:109]
	v_cvt_f32_f16_sdwa v109, v126 dst_sel:DWORD dst_unused:UNUSED_PAD src0_sel:WORD_1
	v_pk_fma_f32 v[26:27], v[100:101], v[26:27], v[120:121]
	v_cvt_f32_f16_e32 v108, v126
	v_cvt_f32_f16_sdwa v121, v127 dst_sel:DWORD dst_unused:UNUSED_PAD src0_sel:WORD_1
	v_cvt_f32_f16_e32 v120, v127
	v_pk_fma_f32 v[20:21], v[104:105], v[20:21], v[108:109]
	v_cvt_f32_f16_sdwa v109, v122 dst_sel:DWORD dst_unused:UNUSED_PAD src0_sel:WORD_1
	v_pk_fma_f32 v[22:23], v[100:101], v[22:23], v[120:121]
	v_cvt_f32_f16_e32 v108, v122
	v_cvt_f32_f16_sdwa v121, v123 dst_sel:DWORD dst_unused:UNUSED_PAD src0_sel:WORD_1
	v_cvt_f32_f16_e32 v120, v123
	s_waitcnt lgkmcnt(0)
	v_mov_b32_e32 v122, v248
	v_mov_b32_e32 v123, v249
	s_waitcnt lgkmcnt(0)
	v_pk_mul_f32 v[16:17], v[16:17], v[122:123] op_sel_hi:[1,0]
	s_nop 0
	v_pk_fma_f32 v[16:17], v[104:105], v[16:17], v[108:109]
	v_cvt_f32_f16_sdwa v109, v110 dst_sel:DWORD dst_unused:UNUSED_PAD src0_sel:WORD_1
	v_cvt_f32_f16_e32 v108, v110
	v_mov_b32_e32 v110, v123
	v_pk_mul_f32 v[18:19], v[18:19], v[122:123] op_sel_hi:[1,0]
	v_pk_mul_f32 v[12:13], v[12:13], v[110:111] op_sel_hi:[1,0]
	v_pk_fma_f32 v[18:19], v[100:101], v[18:19], v[120:121]
	v_cvt_f32_f16_sdwa v121, v111 dst_sel:DWORD dst_unused:UNUSED_PAD src0_sel:WORD_1
	v_cvt_f32_f16_e32 v120, v111
	v_pk_mul_f32 v[14:15], v[14:15], v[110:111] op_sel_hi:[1,0]
	v_pk_fma_f32 v[12:13], v[104:105], v[12:13], v[108:109]
	v_cvt_f32_f16_sdwa v109, v106 dst_sel:DWORD dst_unused:UNUSED_PAD src0_sel:WORD_1
	v_cvt_f32_f16_e32 v108, v106
	v_cvt_f32_f16_sdwa v111, v107 dst_sel:DWORD dst_unused:UNUSED_PAD src0_sel:WORD_1
	v_cvt_f32_f16_e32 v110, v107
	s_waitcnt lgkmcnt(0)
	v_mov_b32_e32 v106, v250
	v_mov_b32_e32 v107, v251
	v_pk_fma_f32 v[14:15], v[100:101], v[14:15], v[120:121]
	s_waitcnt lgkmcnt(0)
	v_pk_mul_f32 v[10:11], v[10:11], v[106:107] op_sel_hi:[1,0]
	v_pk_mul_f32 v[8:9], v[8:9], v[106:107] op_sel_hi:[1,0]
	v_pk_fma_f32 v[10:11], v[100:101], v[10:11], v[110:111]
	v_pk_fma_f32 v[8:9], v[104:105], v[8:9], v[108:109]
	v_cvt_f32_f16_sdwa v109, v102 dst_sel:DWORD dst_unused:UNUSED_PAD src0_sel:WORD_1
	v_cvt_f32_f16_e32 v108, v102
	v_cvt_f32_f16_sdwa v111, v103 dst_sel:DWORD dst_unused:UNUSED_PAD src0_sel:WORD_1
	v_cvt_f32_f16_e32 v110, v103
	v_mov_b32_e32 v102, v107
	v_pk_mul_f32 v[6:7], v[6:7], v[102:103] op_sel_hi:[1,0]
	v_pk_mul_f32 v[4:5], v[4:5], v[102:103] op_sel_hi:[1,0]
	v_pk_fma_f32 v[6:7], v[100:101], v[6:7], v[110:111]
	v_pk_fma_f32 v[4:5], v[104:105], v[4:5], v[108:109]
	s_cbranch_scc1 .LBB0_783
	v_mul_f32_e32 v100, v97, v97
	v_mul_f32_e32 v101, v99, v99
	v_fmac_f32_e32 v100, v96, v96
	v_fmac_f32_e32 v101, v98, v98
	v_add_f32_e32 v100, v100, v101
	v_mul_f32_e32 v101, v161, v161
	v_mul_f32_e32 v102, v163, v163
	v_fmac_f32_e32 v101, v160, v160
	v_fmac_f32_e32 v102, v162, v162
	v_add_f32_e32 v101, v101, v102
	v_add_f32_e32 v100, v100, v101
	v_mul_f32_e32 v101, v85, v85
	v_mul_f32_e32 v102, v87, v87
	v_fmac_f32_e32 v101, v84, v84
	v_fmac_f32_e32 v102, v86, v86
	v_add_f32_e32 v101, v101, v102
	v_add_f32_e32 v100, v100, v101
	v_mul_f32_e32 v101, v33, v33
	v_mul_f32_e32 v102, v35, v35
	v_fmac_f32_e32 v101, v32, v32
	v_fmac_f32_e32 v102, v34, v34
	v_add_f32_e32 v101, v101, v102
	v_add_f32_e32 v100, v100, v101
	v_mov_b32_e32 v101, v100
	s_nop 1
	v_permlane16_swap_b32_e32 v101, v100
	s_waitcnt lgkmcnt(0)
	v_add_f32_e32 v100, v100, v101
	v_mov_b32_e32 v101, v100
	s_nop 1
	v_permlane32_swap_b32_e32 v101, v100
	s_and_saveexec_b64 s[16:17], s[0:1]
	s_cbranch_execz .LBB0_756
	s_lshl_b32 s11, s38, 10
	s_add_i32 s11, s48, s11
	v_lshl_add_u32 v102, v219, 4, s11
	s_waitcnt lgkmcnt(0)
	v_add_f32_e32 v100, v100, v101
	ds_write_b32 v102, v100

; __device__ __forceinline__ unsigned cvt_pk_bf16(float lo, float hi) { unsigned r; asm volatile("v_cvt_pk_bf16_f32 %0, %1, %2" : "=v"(r) : "v"(lo), "v"(hi)); return r; }
;     __device__ __forceinline__ void fused(f32x4 (&acc)[2][2][4][2], const Unit& u, int wr, int wc, int fr, int fq, PG8_LAS unsigned char* lds, int wid, int lane) const {
;     ...
;             for (int n = 0; n < 2; ++n) { sh[n] = (f32x4){0.f, 0.f, 0.f, 0.f}; sg[n] = sh[n];
;                 if (HH) { sh[n] = *(const f32x4*)(shift + (size_t)b * 9216 + c + 4 * n); sg[n] = (*(const f32x4*)(shift + (size_t)b * 9216 + 1024 + c + 4 * n) + 1.0f) * *(const f32x4*)(gpre + c + 4 * n); } }
; #pragma unroll
;             for (int ai = 0; ai < 2; ++ai)
; #pragma unroll
;                 for (int m = 0; m < 4; ++m) { const int r = ai * HALF + wr * 64 + m * 16 + fr; const size_t off = (size_t)(u.pm * BM + r) * 1024 + c;
;                     const f32x4 x0 = acc[ai][bj][m][0], x1 = acc[ai][bj][m][1];
;                     if (XF) { *(f32x4*)(XF + off) = x0; *(f32x4*)(XF + off + 4) = x1; }
;                     else { u32x4v w; w.x = cvt_pk_f16(x0[0], x0[1]); w.y = cvt_pk_f16(x0[2], x0[3]); w.z = cvt_pk_f16(x1[0], x1[1]); w.w = cvt_pk_f16(x1[2], x1[3]); *(u32x4v*)(X + off) = w; }
;                     if (HH) { const float rs = S[r]; const f32x4 o0 = x0 * rs * sg[0] + sh[0], o1 = x1 * rs * sg[1] + sh[1];
;                         u32x4v w; w.x = cvt_pk_bf16(o0[0], o0[1]); w.y = cvt_pk_bf16(o0[2], o0[3]); w.z = cvt_pk_bf16(o1[0], o1[1]); w.w = cvt_pk_bf16(o1[2], o1[3]); *(u32x4v*)(HH + off) = w; } }
.LBB0_790:
	s_and_b64 vcc, exec, s[0:1]
	v_lshl_add_u32 v2, v218, 2, 0
	ds_read_b32 v244, v2 offset:4096
	ds_read_b32 v245, v2 offset:4160
	ds_read_b32 v246, v2 offset:4224
	ds_read_b32 v247, v2 offset:4288
	ds_read_b32 v248, v2 offset:4608
	ds_read_b32 v249, v2 offset:4672
	ds_read_b32 v250, v2 offset:4736
	ds_read_b32 v251, v2 offset:4800
	v_lshl_add_u64 v[120:121], v[120:121], 1, s[12:13]
	s_cbranch_vccnz .LBB0_792
	s_waitcnt lgkmcnt(0)
	v_mov_b32_e32 v126, v244
	s_waitcnt lgkmcnt(0)
	v_pk_mul_f32 v[96:97], v[96:97], v[126:127] op_sel_hi:[1,0]
	v_pk_mul_f32 v[98:99], v[98:99], v[126:127] op_sel_hi:[1,0]
	v_pk_mul_f32 v[128:129], v[160:161], v[126:127] op_sel_hi:[1,0]
	v_pk_mul_f32 v[126:127], v[162:163], v[126:127] op_sel_hi:[1,0]
	v_pk_fma_f32 v[98:99], v[164:165], v[98:99], v[106:107]
	v_pk_fma_f32 v[96:97], v[142:143], v[96:97], v[104:105]
	v_pk_fma_f32 v[126:127], v[168:169], v[126:127], v[102:103]
	v_pk_fma_f32 v[128:129], v[166:167], v[128:129], v[100:101]
	v_cvt_pk_bf16_f32 v96, v96, v97
	v_cvt_pk_bf16_f32 v97, v98, v99
	s_nop 0
	v_cvt_pk_bf16_f32 v98, v128, v129
	v_cvt_pk_bf16_f32 v99, v126, v127
	flat_store_dwordx4 v[120:121], v[96:99]

; __device__ __forceinline__ unsigned cvt_pk_bf16(float lo, float hi) { unsigned r; asm volatile("v_cvt_pk_bf16_f32 %0, %1, %2" : "=v"(r) : "v"(lo), "v"(hi)); return r; }
;     __device__ __forceinline__ void fused(f32x4 (&acc)[2][2][4][2], const Unit& u, int wr, int wc, int fr, int fq, PG8_LAS unsigned char* lds, int wid, int lane) const {
;     ...
;             for (int n = 0; n < 2; ++n) { sh[n] = (f32x4){0.f, 0.f, 0.f, 0.f}; sg[n] = sh[n];
;                 if (HH) { sh[n] = *(const f32x4*)(shift + (size_t)b * 9216 + c + 4 * n); sg[n] = (*(const f32x4*)(shift + (size_t)b * 9216 + 1024 + c + 4 * n) + 1.0f) * *(const f32x4*)(gpre + c + 4 * n); } }
; #pragma unroll
;             for (int ai = 0; ai < 2; ++ai)
; #pragma unroll
;                 for (int m = 0; m < 4; ++m) { const int r = ai * HALF + wr * 64 + m * 16 + fr; const size_t off = (size_t)(u.pm * BM + r) * 1024 + c;
;                     const f32x4 x0 = acc[ai][bj][m][0], x1 = acc[ai][bj][m][1];
;                     if (XF) { *(f32x4*)(XF + off) = x0; *(f32x4*)(XF + off + 4) = x1; }
;                     else { u32x4v w; w.x = cvt_pk_f16(x0[0], x0[1]); w.y = cvt_pk_f16(x0[2], x0[3]); w.z = cvt_pk_f16(x1[0], x1[1]); w.w = cvt_pk_f16(x1[2], x1[3]); *(u32x4v*)(X + off) = w; }
;                     if (HH) { const float rs = S[r]; const f32x4 o0 = x0 * rs * sg[0] + sh[0], o1 = x1 * rs * sg[1] + sh[1];
;                         u32x4v w; w.x = cvt_pk_bf16(o0[0], o0[1]); w.y = cvt_pk_bf16(o0[2], o0[3]); w.z = cvt_pk_bf16(o1[0], o1[1]); w.w = cvt_pk_bf16(o1[2], o1[3]); *(u32x4v*)(HH + off) = w; } }
.LBB0_795:
	s_and_b64 vcc, exec, s[0:1]
	v_lshl_add_u64 v[96:97], v[96:97], 1, s[12:13]
	s_cbranch_vccnz .LBB0_797
	s_waitcnt lgkmcnt(0)
	v_mov_b32_e32 v128, v245
	s_waitcnt lgkmcnt(0)
	v_pk_mul_f32 v[88:89], v[88:89], v[128:129] op_sel_hi:[1,0]
	v_pk_mul_f32 v[90:91], v[90:91], v[128:129] op_sel_hi:[1,0]
	v_pk_mul_f32 v[130:131], v[156:157], v[128:129] op_sel_hi:[1,0]
	v_pk_mul_f32 v[128:129], v[158:159], v[128:129] op_sel_hi:[1,0]
	v_pk_fma_f32 v[90:91], v[164:165], v[90:91], v[106:107]
	v_pk_fma_f32 v[88:89], v[142:143], v[88:89], v[104:105]
	v_pk_fma_f32 v[128:129], v[168:169], v[128:129], v[102:103]
	v_pk_fma_f32 v[130:131], v[166:167], v[130:131], v[100:101]
	v_cvt_pk_bf16_f32 v88, v88, v89
	v_cvt_pk_bf16_f32 v89, v90, v91
	s_nop 0
	v_cvt_pk_bf16_f32 v90, v130, v131
	v_cvt_pk_bf16_f32 v91, v128, v129
	flat_store_dwordx4 v[96:97], v[88:91]

; __device__ __forceinline__ unsigned cvt_pk_bf16(float lo, float hi) { unsigned r; asm volatile("v_cvt_pk_bf16_f32 %0, %1, %2" : "=v"(r) : "v"(lo), "v"(hi)); return r; }
;     __device__ __forceinline__ void fused(f32x4 (&acc)[2][2][4][2], const Unit& u, int wr, int wc, int fr, int fq, PG8_LAS unsigned char* lds, int wid, int lane) const {
;     ...
;             for (int n = 0; n < 2; ++n) { sh[n] = (f32x4){0.f, 0.f, 0.f, 0.f}; sg[n] = sh[n];
;                 if (HH) { sh[n] = *(const f32x4*)(shift + (size_t)b * 9216 + c + 4 * n); sg[n] = (*(const f32x4*)(shift + (size_t)b * 9216 + 1024 + c + 4 * n) + 1.0f) * *(const f32x4*)(gpre + c + 4 * n); } }
; #pragma unroll
;             for (int ai = 0; ai < 2; ++ai)
; #pragma unroll
;                 for (int m = 0; m < 4; ++m) { const int r = ai * HALF + wr * 64 + m * 16 + fr; const size_t off = (size_t)(u.pm * BM + r) * 1024 + c;
;                     const f32x4 x0 = acc[ai][bj][m][0], x1 = acc[ai][bj][m][1];
;                     if (XF) { *(f32x4*)(XF + off) = x0; *(f32x4*)(XF + off + 4) = x1; }
;                     else { u32x4v w; w.x = cvt_pk_f16(x0[0], x0[1]); w.y = cvt_pk_f16(x0[2], x0[3]); w.z = cvt_pk_f16(x1[0], x1[1]); w.w = cvt_pk_f16(x1[2], x1[3]); *(u32x4v*)(X + off) = w; }
;                     if (HH) { const float rs = S[r]; const f32x4 o0 = x0 * rs * sg[0] + sh[0], o1 = x1 * rs * sg[1] + sh[1];
;                         u32x4v w; w.x = cvt_pk_bf16(o0[0], o0[1]); w.y = cvt_pk_bf16(o0[2], o0[3]); w.z = cvt_pk_bf16(o1[0], o1[1]); w.w = cvt_pk_bf16(o1[2], o1[3]); *(u32x4v*)(HH + off) = w; } }
.LBB0_800:
	s_and_b64 vcc, exec, s[0:1]
	v_lshl_add_u64 v[88:89], v[88:89], 1, s[12:13]
	s_cbranch_vccnz .LBB0_802
	s_waitcnt lgkmcnt(0)
	v_mov_b32_e32 v90, v246
	s_waitcnt lgkmcnt(0)
	v_pk_mul_f32 v[92:93], v[92:93], v[90:91] op_sel_hi:[1,0]
	v_pk_mul_f32 v[94:95], v[94:95], v[90:91] op_sel_hi:[1,0]
	v_pk_mul_f32 v[132:133], v[152:153], v[90:91] op_sel_hi:[1,0]
	v_pk_mul_f32 v[90:91], v[154:155], v[90:91] op_sel_hi:[1,0]
	v_pk_fma_f32 v[92:93], v[142:143], v[92:93], v[104:105]
	v_pk_fma_f32 v[94:95], v[164:165], v[94:95], v[106:107]
	v_pk_fma_f32 v[134:135], v[168:169], v[90:91], v[102:103]
	v_pk_fma_f32 v[132:133], v[166:167], v[132:133], v[100:101]
	v_cvt_pk_bf16_f32 v90, v92, v93
	v_cvt_pk_bf16_f32 v91, v94, v95
	s_nop 0
	v_cvt_pk_bf16_f32 v92, v132, v133
	v_cvt_pk_bf16_f32 v93, v134, v135
	flat_store_dwordx4 v[88:89], v[90:93]

; __device__ __forceinline__ unsigned cvt_pk_bf16(float lo, float hi) { unsigned r; asm volatile("v_cvt_pk_bf16_f32 %0, %1, %2" : "=v"(r) : "v"(lo), "v"(hi)); return r; }
;     __device__ __forceinline__ void fused(f32x4 (&acc)[2][2][4][2], const Unit& u, int wr, int wc, int fr, int fq, PG8_LAS unsigned char* lds, int wid, int lane) const {
;     ...
;             for (int n = 0; n < 2; ++n) { sh[n] = (f32x4){0.f, 0.f, 0.f, 0.f}; sg[n] = sh[n];
;                 if (HH) { sh[n] = *(const f32x4*)(shift + (size_t)b * 9216 + c + 4 * n); sg[n] = (*(const f32x4*)(shift + (size_t)b * 9216 + 1024 + c + 4 * n) + 1.0f) * *(const f32x4*)(gpre + c + 4 * n); } }
; #pragma unroll
;             for (int ai = 0; ai < 2; ++ai)
; #pragma unroll
;                 for (int m = 0; m < 4; ++m) { const int r = ai * HALF + wr * 64 + m * 16 + fr; const size_t off = (size_t)(u.pm * BM + r) * 1024 + c;
;                     const f32x4 x0 = acc[ai][bj][m][0], x1 = acc[ai][bj][m][1];
;                     if (XF) { *(f32x4*)(XF + off) = x0; *(f32x4*)(XF + off + 4) = x1; }
;                     else { u32x4v w; w.x = cvt_pk_f16(x0[0], x0[1]); w.y = cvt_pk_f16(x0[2], x0[3]); w.z = cvt_pk_f16(x1[0], x1[1]); w.w = cvt_pk_f16(x1[2], x1[3]); *(u32x4v*)(X + off) = w; }
;                     if (HH) { const float rs = S[r]; const f32x4 o0 = x0 * rs * sg[0] + sh[0], o1 = x1 * rs * sg[1] + sh[1];
;                         u32x4v w; w.x = cvt_pk_bf16(o0[0], o0[1]); w.y = cvt_pk_bf16(o0[2], o0[3]); w.z = cvt_pk_bf16(o1[0], o1[1]); w.w = cvt_pk_bf16(o1[2], o1[3]); *(u32x4v*)(HH + off) = w; } }
.LBB0_805:
	s_and_b64 vcc, exec, s[0:1]
	v_lshl_add_u64 v[90:91], v[90:91], 1, s[12:13]
	s_cbranch_vccnz .LBB0_807
	s_waitcnt lgkmcnt(0)
	v_mov_b32_e32 v132, v247
	s_waitcnt lgkmcnt(0)
	v_pk_mul_f32 v[72:73], v[72:73], v[132:133] op_sel_hi:[1,0]
	v_pk_mul_f32 v[74:75], v[74:75], v[132:133] op_sel_hi:[1,0]
	v_pk_mul_f32 v[134:135], v[148:149], v[132:133] op_sel_hi:[1,0]
	v_pk_mul_f32 v[132:133], v[150:151], v[132:133] op_sel_hi:[1,0]
	v_pk_fma_f32 v[74:75], v[164:165], v[74:75], v[106:107]
	v_pk_fma_f32 v[72:73], v[142:143], v[72:73], v[104:105]
	v_pk_fma_f32 v[132:133], v[168:169], v[132:133], v[102:103]
	v_pk_fma_f32 v[134:135], v[166:167], v[134:135], v[100:101]
	v_cvt_pk_bf16_f32 v72, v72, v73
	v_cvt_pk_bf16_f32 v73, v74, v75
	s_nop 0
	v_cvt_pk_bf16_f32 v74, v134, v135
	v_cvt_pk_bf16_f32 v75, v132, v133
	flat_store_dwordx4 v[90:91], v[72:75]

; __device__ __forceinline__ unsigned cvt_pk_bf16(float lo, float hi) { unsigned r; asm volatile("v_cvt_pk_bf16_f32 %0, %1, %2" : "=v"(r) : "v"(lo), "v"(hi)); return r; }
;     __device__ __forceinline__ void fused(f32x4 (&acc)[2][2][4][2], const Unit& u, int wr, int wc, int fr, int fq, PG8_LAS unsigned char* lds, int wid, int lane) const {
;     ...
;             for (int n = 0; n < 2; ++n) { sh[n] = (f32x4){0.f, 0.f, 0.f, 0.f}; sg[n] = sh[n];
;                 if (HH) { sh[n] = *(const f32x4*)(shift + (size_t)b * 9216 + c + 4 * n); sg[n] = (*(const f32x4*)(shift + (size_t)b * 9216 + 1024 + c + 4 * n) + 1.0f) * *(const f32x4*)(gpre + c + 4 * n); } }
; #pragma unroll
;             for (int ai = 0; ai < 2; ++ai)
; #pragma unroll
;                 for (int m = 0; m < 4; ++m) { const int r = ai * HALF + wr * 64 + m * 16 + fr; const size_t off = (size_t)(u.pm * BM + r) * 1024 + c;
;                     const f32x4 x0 = acc[ai][bj][m][0], x1 = acc[ai][bj][m][1];
;                     if (XF) { *(f32x4*)(XF + off) = x0; *(f32x4*)(XF + off + 4) = x1; }
;                     else { u32x4v w; w.x = cvt_pk_f16(x0[0], x0[1]); w.y = cvt_pk_f16(x0[2], x0[3]); w.z = cvt_pk_f16(x1[0], x1[1]); w.w = cvt_pk_f16(x1[2], x1[3]); *(u32x4v*)(X + off) = w; }
;                     if (HH) { const float rs = S[r]; const f32x4 o0 = x0 * rs * sg[0] + sh[0], o1 = x1 * rs * sg[1] + sh[1];
;                         u32x4v w; w.x = cvt_pk_bf16(o0[0], o0[1]); w.y = cvt_pk_bf16(o0[2], o0[3]); w.z = cvt_pk_bf16(o1[0], o1[1]); w.w = cvt_pk_bf16(o1[2], o1[3]); *(u32x4v*)(HH + off) = w; } }
.LBB0_810:
	s_and_b64 vcc, exec, s[0:1]
	v_lshl_add_u64 v[72:73], v[72:73], 1, s[12:13]
	s_cbranch_vccnz .LBB0_812
	s_waitcnt lgkmcnt(0)
	v_mov_b32_e32 v74, v248
	s_waitcnt lgkmcnt(0)
	v_pk_mul_f32 v[80:81], v[80:81], v[74:75] op_sel_hi:[1,0]
	v_pk_mul_f32 v[82:83], v[82:83], v[74:75] op_sel_hi:[1,0]
	v_pk_mul_f32 v[140:141], v[144:145], v[74:75] op_sel_hi:[1,0]
	v_pk_mul_f32 v[74:75], v[146:147], v[74:75] op_sel_hi:[1,0]
	v_pk_fma_f32 v[82:83], v[164:165], v[82:83], v[106:107]
	v_pk_fma_f32 v[80:81], v[142:143], v[80:81], v[104:105]
	v_pk_fma_f32 v[74:75], v[168:169], v[74:75], v[102:103]
	v_pk_fma_f32 v[140:141], v[166:167], v[140:141], v[100:101]
	v_cvt_pk_bf16_f32 v80, v80, v81
	v_cvt_pk_bf16_f32 v81, v82, v83
	s_nop 0
	v_cvt_pk_bf16_f32 v82, v140, v141
	v_cvt_pk_bf16_f32 v83, v74, v75
	flat_store_dwordx4 v[72:73], v[80:83]

; __device__ __forceinline__ unsigned cvt_pk_bf16(float lo, float hi) { unsigned r; asm volatile("v_cvt_pk_bf16_f32 %0, %1, %2" : "=v"(r) : "v"(lo), "v"(hi)); return r; }
;     __device__ __forceinline__ void fused(f32x4 (&acc)[2][2][4][2], const Unit& u, int wr, int wc, int fr, int fq, PG8_LAS unsigned char* lds, int wid, int lane) const {
;     ...
;             for (int n = 0; n < 2; ++n) { sh[n] = (f32x4){0.f, 0.f, 0.f, 0.f}; sg[n] = sh[n];
;                 if (HH) { sh[n] = *(const f32x4*)(shift + (size_t)b * 9216 + c + 4 * n); sg[n] = (*(const f32x4*)(shift + (size_t)b * 9216 + 1024 + c + 4 * n) + 1.0f) * *(const f32x4*)(gpre + c + 4 * n); } }
; #pragma unroll
;             for (int ai = 0; ai < 2; ++ai)
; #pragma unroll
;                 for (int m = 0; m < 4; ++m) { const int r = ai * HALF + wr * 64 + m * 16 + fr; const size_t off = (size_t)(u.pm * BM + r) * 1024 + c;
;                     const f32x4 x0 = acc[ai][bj][m][0], x1 = acc[ai][bj][m][1];
;                     if (XF) { *(f32x4*)(XF + off) = x0; *(f32x4*)(XF + off + 4) = x1; }
;                     else { u32x4v w; w.x = cvt_pk_f16(x0[0], x0[1]); w.y = cvt_pk_f16(x0[2], x0[3]); w.z = cvt_pk_f16(x1[0], x1[1]); w.w = cvt_pk_f16(x1[2], x1[3]); *(u32x4v*)(X + off) = w; }
;                     if (HH) { const float rs = S[r]; const f32x4 o0 = x0 * rs * sg[0] + sh[0], o1 = x1 * rs * sg[1] + sh[1];
;                         u32x4v w; w.x = cvt_pk_bf16(o0[0], o0[1]); w.y = cvt_pk_bf16(o0[2], o0[3]); w.z = cvt_pk_bf16(o1[0], o1[1]); w.w = cvt_pk_bf16(o1[2], o1[3]); *(u32x4v*)(HH + off) = w; } }
.LBB0_815:
	s_and_b64 vcc, exec, s[0:1]
	v_lshl_add_u64 v[74:75], v[74:75], 1, s[12:13]
	s_cbranch_vccnz .LBB0_817
	s_waitcnt lgkmcnt(0)
	v_mov_b32_e32 v80, v249
	s_waitcnt lgkmcnt(0)
	v_pk_mul_f32 v[64:65], v[64:65], v[80:81] op_sel_hi:[1,0]
	v_pk_mul_f32 v[66:67], v[66:67], v[80:81] op_sel_hi:[1,0]
	v_pk_mul_f32 v[136:137], v[136:137], v[80:81] op_sel_hi:[1,0]
	v_pk_mul_f32 v[80:81], v[138:139], v[80:81] op_sel_hi:[1,0]
	v_pk_fma_f32 v[66:67], v[164:165], v[66:67], v[106:107]
	v_pk_fma_f32 v[64:65], v[142:143], v[64:65], v[104:105]
	v_pk_fma_f32 v[80:81], v[168:169], v[80:81], v[102:103]
	v_pk_fma_f32 v[136:137], v[166:167], v[136:137], v[100:101]
	v_cvt_pk_bf16_f32 v64, v64, v65
	v_cvt_pk_bf16_f32 v65, v66, v67
	s_nop 0
	v_cvt_pk_bf16_f32 v66, v136, v137
	v_cvt_pk_bf16_f32 v67, v80, v81
	flat_store_dwordx4 v[74:75], v[64:67]

; __device__ __forceinline__ unsigned cvt_pk_bf16(float lo, float hi) { unsigned r; asm volatile("v_cvt_pk_bf16_f32 %0, %1, %2" : "=v"(r) : "v"(lo), "v"(hi)); return r; }
;     __device__ __forceinline__ void fused(f32x4 (&acc)[2][2][4][2], const Unit& u, int wr, int wc, int fr, int fq, PG8_LAS unsigned char* lds, int wid, int lane) const {
;     ...
;             for (int n = 0; n < 2; ++n) { sh[n] = (f32x4){0.f, 0.f, 0.f, 0.f}; sg[n] = sh[n];
;                 if (HH) { sh[n] = *(const f32x4*)(shift + (size_t)b * 9216 + c + 4 * n); sg[n] = (*(const f32x4*)(shift + (size_t)b * 9216 + 1024 + c + 4 * n) + 1.0f) * *(const f32x4*)(gpre + c + 4 * n); } }
; #pragma unroll
;             for (int ai = 0; ai < 2; ++ai)
; #pragma unroll
;                 for (int m = 0; m < 4; ++m) { const int r = ai * HALF + wr * 64 + m * 16 + fr; const size_t off = (size_t)(u.pm * BM + r) * 1024 + c;
;                     const f32x4 x0 = acc[ai][bj][m][0], x1 = acc[ai][bj][m][1];
;                     if (XF) { *(f32x4*)(XF + off) = x0; *(f32x4*)(XF + off + 4) = x1; }
;                     else { u32x4v w; w.x = cvt_pk_f16(x0[0], x0[1]); w.y = cvt_pk_f16(x0[2], x0[3]); w.z = cvt_pk_f16(x1[0], x1[1]); w.w = cvt_pk_f16(x1[2], x1[3]); *(u32x4v*)(X + off) = w; }
;                     if (HH) { const float rs = S[r]; const f32x4 o0 = x0 * rs * sg[0] + sh[0], o1 = x1 * rs * sg[1] + sh[1];
;                         u32x4v w; w.x = cvt_pk_bf16(o0[0], o0[1]); w.y = cvt_pk_bf16(o0[2], o0[3]); w.z = cvt_pk_bf16(o1[0], o1[1]); w.w = cvt_pk_bf16(o1[2], o1[3]); *(u32x4v*)(HH + off) = w; } }
.LBB0_820:
	s_and_b64 vcc, exec, s[0:1]
	v_lshl_add_u64 v[80:81], v[64:65], 1, s[12:13]
	s_cbranch_vccnz .LBB0_822
	s_waitcnt lgkmcnt(0)
	v_mov_b32_e32 v64, v250
	s_waitcnt lgkmcnt(0)
	v_pk_mul_f32 v[66:67], v[68:69], v[64:65] op_sel_hi:[1,0]
	v_pk_mul_f32 v[68:69], v[70:71], v[64:65] op_sel_hi:[1,0]
	v_pk_mul_f32 v[70:71], v[116:117], v[64:65] op_sel_hi:[1,0]
	v_pk_mul_f32 v[64:65], v[118:119], v[64:65] op_sel_hi:[1,0]
	v_pk_fma_f32 v[66:67], v[142:143], v[66:67], v[104:105]
	v_pk_fma_f32 v[68:69], v[164:165], v[68:69], v[106:107]
	v_pk_fma_f32 v[116:117], v[168:169], v[64:65], v[102:103]
	v_pk_fma_f32 v[70:71], v[166:167], v[70:71], v[100:101]
	v_cvt_pk_bf16_f32 v64, v66, v67
	v_cvt_pk_bf16_f32 v65, v68, v69
	s_nop 0
	v_cvt_pk_bf16_f32 v66, v70, v71
	v_cvt_pk_bf16_f32 v67, v116, v117
	flat_store_dwordx4 v[80:81], v[64:67]

; __device__ __forceinline__ unsigned cvt_pk_bf16(float lo, float hi) { unsigned r; asm volatile("v_cvt_pk_bf16_f32 %0, %1, %2" : "=v"(r) : "v"(lo), "v"(hi)); return r; }
;     __device__ __forceinline__ void fused(f32x4 (&acc)[2][2][4][2], const Unit& u, int wr, int wc, int fr, int fq, PG8_LAS unsigned char* lds, int wid, int lane) const {
;     ...
;             for (int n = 0; n < 2; ++n) { sh[n] = (f32x4){0.f, 0.f, 0.f, 0.f}; sg[n] = sh[n];
;                 if (HH) { sh[n] = *(const f32x4*)(shift + (size_t)b * 9216 + c + 4 * n); sg[n] = (*(const f32x4*)(shift + (size_t)b * 9216 + 1024 + c + 4 * n) + 1.0f) * *(const f32x4*)(gpre + c + 4 * n); } }
; #pragma unroll
;             for (int ai = 0; ai < 2; ++ai)
; #pragma unroll
;                 for (int m = 0; m < 4; ++m) { const int r = ai * HALF + wr * 64 + m * 16 + fr; const size_t off = (size_t)(u.pm * BM + r) * 1024 + c;
;                     const f32x4 x0 = acc[ai][bj][m][0], x1 = acc[ai][bj][m][1];
;                     if (XF) { *(f32x4*)(XF + off) = x0; *(f32x4*)(XF + off + 4) = x1; }
;                     else { u32x4v w; w.x = cvt_pk_f16(x0[0], x0[1]); w.y = cvt_pk_f16(x0[2], x0[3]); w.z = cvt_pk_f16(x1[0], x1[1]); w.w = cvt_pk_f16(x1[2], x1[3]); *(u32x4v*)(X + off) = w; }
;                     if (HH) { const float rs = S[r]; const f32x4 o0 = x0 * rs * sg[0] + sh[0], o1 = x1 * rs * sg[1] + sh[1];
;                         u32x4v w; w.x = cvt_pk_bf16(o0[0], o0[1]); w.y = cvt_pk_bf16(o0[2], o0[3]); w.z = cvt_pk_bf16(o1[0], o1[1]); w.w = cvt_pk_bf16(o1[2], o1[3]); *(u32x4v*)(HH + off) = w; } }
.LBB0_825:
	s_and_b64 vcc, exec, s[0:1]
	s_nop 0
	v_lshl_add_u64 v[68:69], v[64:65], 1, s[12:13]
	s_cbranch_vccnz .LBB0_827
	s_waitcnt lgkmcnt(0)
	v_mov_b32_e32 v64, v251
	s_waitcnt lgkmcnt(0)
	v_pk_mul_f32 v[52:53], v[52:53], v[64:65] op_sel_hi:[1,0]
	v_pk_mul_f32 v[54:55], v[54:55], v[64:65] op_sel_hi:[1,0]
	v_pk_mul_f32 v[66:67], v[112:113], v[64:65] op_sel_hi:[1,0]
	v_pk_mul_f32 v[64:65], v[114:115], v[64:65] op_sel_hi:[1,0]
	v_pk_fma_f32 v[54:55], v[164:165], v[54:55], v[106:107]
	v_pk_fma_f32 v[52:53], v[142:143], v[52:53], v[104:105]
	v_pk_fma_f32 v[64:65], v[168:169], v[64:65], v[102:103]
	v_pk_fma_f32 v[66:67], v[166:167], v[66:67], v[100:101]
	v_cvt_pk_bf16_f32 v52, v52, v53
	v_cvt_pk_bf16_f32 v53, v54, v55
	s_nop 0
	v_cvt_pk_bf16_f32 v54, v66, v67
	v_cvt_pk_bf16_f32 v55, v64, v65
	flat_store_dwordx4 v[68:69], v[52:55]

; __device__ __forceinline__ unsigned cvt_pk_bf16(float lo, float hi) { unsigned r; asm volatile("v_cvt_pk_bf16_f32 %0, %1, %2" : "=v"(r) : "v"(lo), "v"(hi)); return r; }
;     __device__ __forceinline__ void fused(f32x4 (&acc)[2][2][4][2], const Unit& u, int wr, int wc, int fr, int fq, PG8_LAS unsigned char* lds, int wid, int lane) const {
;     ...
;             for (int n = 0; n < 2; ++n) { sh[n] = (f32x4){0.f, 0.f, 0.f, 0.f}; sg[n] = sh[n];
;                 if (HH) { sh[n] = *(const f32x4*)(shift + (size_t)b * 9216 + c + 4 * n); sg[n] = (*(const f32x4*)(shift + (size_t)b * 9216 + 1024 + c + 4 * n) + 1.0f) * *(const f32x4*)(gpre + c + 4 * n); } }
; #pragma unroll
;             for (int ai = 0; ai < 2; ++ai)
; #pragma unroll
;                 for (int m = 0; m < 4; ++m) { const int r = ai * HALF + wr * 64 + m * 16 + fr; const size_t off = (size_t)(u.pm * BM + r) * 1024 + c;
;                     const f32x4 x0 = acc[ai][bj][m][0], x1 = acc[ai][bj][m][1];
;                     if (XF) { *(f32x4*)(XF + off) = x0; *(f32x4*)(XF + off + 4) = x1; }
;                     else { u32x4v w; w.x = cvt_pk_f16(x0[0], x0[1]); w.y = cvt_pk_f16(x0[2], x0[3]); w.z = cvt_pk_f16(x1[0], x1[1]); w.w = cvt_pk_f16(x1[2], x1[3]); *(u32x4v*)(X + off) = w; }
;                     if (HH) { const float rs = S[r]; const f32x4 o0 = x0 * rs * sg[0] + sh[0], o1 = x1 * rs * sg[1] + sh[1];
;                         u32x4v w; w.x = cvt_pk_bf16(o0[0], o0[1]); w.y = cvt_pk_bf16(o0[2], o0[3]); w.z = cvt_pk_bf16(o1[0], o1[1]); w.w = cvt_pk_bf16(o1[2], o1[3]); *(u32x4v*)(HH + off) = w; } }
.LBB0_834:
	s_and_b64 vcc, exec, s[0:1]
	s_cbranch_vccnz .LBB0_836
	s_waitcnt lgkmcnt(0)
	v_mov_b32_e32 v106, v244
	s_waitcnt lgkmcnt(0)
	v_pk_mul_f32 v[32:33], v[32:33], v[106:107] op_sel_hi:[1,0]
	v_pk_mul_f32 v[34:35], v[34:35], v[106:107] op_sel_hi:[1,0]
	v_pk_mul_f32 v[84:85], v[84:85], v[106:107] op_sel_hi:[1,0]
	v_pk_mul_f32 v[86:87], v[86:87], v[106:107] op_sel_hi:[1,0]
	v_pk_fma_f32 v[106:107], v[104:105], v[34:35], v[54:55]
	v_pk_fma_f32 v[34:35], v[102:103], v[32:33], v[52:53]
	v_pk_fma_f32 v[86:87], v[100:101], v[86:87], v[66:67]
	v_pk_fma_f32 v[84:85], v[0:1], v[84:85], v[64:65]
	s_nop 0
	v_cvt_pk_bf16_f32 v32, v84, v85
	v_cvt_pk_bf16_f32 v33, v86, v87
	v_cvt_pk_bf16_f32 v34, v34, v35
	v_cvt_pk_bf16_f32 v35, v106, v107
	flat_store_dwordx4 v[120:121], v[32:35] offset:256

; __device__ __forceinline__ unsigned cvt_pk_bf16(float lo, float hi) { unsigned r; asm volatile("v_cvt_pk_bf16_f32 %0, %1, %2" : "=v"(r) : "v"(lo), "v"(hi)); return r; }
;     __device__ __forceinline__ void fused(f32x4 (&acc)[2][2][4][2], const Unit& u, int wr, int wc, int fr, int fq, PG8_LAS unsigned char* lds, int wid, int lane) const {
;     ...
;             for (int n = 0; n < 2; ++n) { sh[n] = (f32x4){0.f, 0.f, 0.f, 0.f}; sg[n] = sh[n];
;                 if (HH) { sh[n] = *(const f32x4*)(shift + (size_t)b * 9216 + c + 4 * n); sg[n] = (*(const f32x4*)(shift + (size_t)b * 9216 + 1024 + c + 4 * n) + 1.0f) * *(const f32x4*)(gpre + c + 4 * n); } }
; #pragma unroll
;             for (int ai = 0; ai < 2; ++ai)
; #pragma unroll
;                 for (int m = 0; m < 4; ++m) { const int r = ai * HALF + wr * 64 + m * 16 + fr; const size_t off = (size_t)(u.pm * BM + r) * 1024 + c;
;                     const f32x4 x0 = acc[ai][bj][m][0], x1 = acc[ai][bj][m][1];
;                     if (XF) { *(f32x4*)(XF + off) = x0; *(f32x4*)(XF + off + 4) = x1; }
;                     else { u32x4v w; w.x = cvt_pk_f16(x0[0], x0[1]); w.y = cvt_pk_f16(x0[2], x0[3]); w.z = cvt_pk_f16(x1[0], x1[1]); w.w = cvt_pk_f16(x1[2], x1[3]); *(u32x4v*)(X + off) = w; }
;                     if (HH) { const float rs = S[r]; const f32x4 o0 = x0 * rs * sg[0] + sh[0], o1 = x1 * rs * sg[1] + sh[1];
;                         u32x4v w; w.x = cvt_pk_bf16(o0[0], o0[1]); w.y = cvt_pk_bf16(o0[2], o0[3]); w.z = cvt_pk_bf16(o1[0], o1[1]); w.w = cvt_pk_bf16(o1[2], o1[3]); *(u32x4v*)(HH + off) = w; } }
.LBB0_839:
	s_and_b64 vcc, exec, s[0:1]
	s_cbranch_vccnz .LBB0_841
	s_waitcnt lgkmcnt(0)
	v_mov_b32_e32 v32, v245
	s_waitcnt lgkmcnt(0)
	v_pk_mul_f32 v[34:35], v[76:77], v[32:33] op_sel_hi:[1,0]
	v_pk_mul_f32 v[76:77], v[78:79], v[32:33] op_sel_hi:[1,0]
	v_pk_mul_f32 v[28:29], v[28:29], v[32:33] op_sel_hi:[1,0]
	v_pk_mul_f32 v[30:31], v[30:31], v[32:33] op_sel_hi:[1,0]
	v_pk_fma_f32 v[32:33], v[100:101], v[76:77], v[66:67]
	v_pk_fma_f32 v[76:77], v[104:105], v[30:31], v[54:55]
	v_pk_fma_f32 v[30:31], v[102:103], v[28:29], v[52:53]
	v_pk_fma_f32 v[34:35], v[0:1], v[34:35], v[64:65]
	s_nop 0
	v_cvt_pk_bf16_f32 v28, v34, v35
	v_cvt_pk_bf16_f32 v29, v32, v33
	v_cvt_pk_bf16_f32 v30, v30, v31
	v_cvt_pk_bf16_f32 v31, v76, v77
	flat_store_dwordx4 v[96:97], v[28:31] offset:256

; __device__ __forceinline__ unsigned cvt_pk_bf16(float lo, float hi) { unsigned r; asm volatile("v_cvt_pk_bf16_f32 %0, %1, %2" : "=v"(r) : "v"(lo), "v"(hi)); return r; }
;     __device__ __forceinline__ void fused(f32x4 (&acc)[2][2][4][2], const Unit& u, int wr, int wc, int fr, int fq, PG8_LAS unsigned char* lds, int wid, int lane) const {
;     ...
;             for (int n = 0; n < 2; ++n) { sh[n] = (f32x4){0.f, 0.f, 0.f, 0.f}; sg[n] = sh[n];
;                 if (HH) { sh[n] = *(const f32x4*)(shift + (size_t)b * 9216 + c + 4 * n); sg[n] = (*(const f32x4*)(shift + (size_t)b * 9216 + 1024 + c + 4 * n) + 1.0f) * *(const f32x4*)(gpre + c + 4 * n); } }
; #pragma unroll
;             for (int ai = 0; ai < 2; ++ai)
; #pragma unroll
;                 for (int m = 0; m < 4; ++m) { const int r = ai * HALF + wr * 64 + m * 16 + fr; const size_t off = (size_t)(u.pm * BM + r) * 1024 + c;
;                     const f32x4 x0 = acc[ai][bj][m][0], x1 = acc[ai][bj][m][1];
;                     if (XF) { *(f32x4*)(XF + off) = x0; *(f32x4*)(XF + off + 4) = x1; }
;                     else { u32x4v w; w.x = cvt_pk_f16(x0[0], x0[1]); w.y = cvt_pk_f16(x0[2], x0[3]); w.z = cvt_pk_f16(x1[0], x1[1]); w.w = cvt_pk_f16(x1[2], x1[3]); *(u32x4v*)(X + off) = w; }
;                     if (HH) { const float rs = S[r]; const f32x4 o0 = x0 * rs * sg[0] + sh[0], o1 = x1 * rs * sg[1] + sh[1];
;                         u32x4v w; w.x = cvt_pk_bf16(o0[0], o0[1]); w.y = cvt_pk_bf16(o0[2], o0[3]); w.z = cvt_pk_bf16(o1[0], o1[1]); w.w = cvt_pk_bf16(o1[2], o1[3]); *(u32x4v*)(HH + off) = w; } }
.LBB0_844:
	s_and_b64 vcc, exec, s[0:1]
	s_cbranch_vccnz .LBB0_846
	s_waitcnt lgkmcnt(0)
	v_mov_b32_e32 v28, v246
	s_waitcnt lgkmcnt(0)
	v_pk_mul_f32 v[32:33], v[62:63], v[28:29] op_sel_hi:[1,0]
	v_pk_mul_f32 v[24:25], v[24:25], v[28:29] op_sel_hi:[1,0]
	v_pk_mul_f32 v[26:27], v[26:27], v[28:29] op_sel_hi:[1,0]
	v_pk_mul_f32 v[30:31], v[60:61], v[28:29] op_sel_hi:[1,0]
	v_pk_fma_f32 v[28:29], v[100:101], v[32:33], v[66:67]
	v_pk_fma_f32 v[32:33], v[104:105], v[26:27], v[54:55]
	v_pk_fma_f32 v[26:27], v[102:103], v[24:25], v[52:53]
	v_pk_fma_f32 v[30:31], v[0:1], v[30:31], v[64:65]
	s_nop 0
	v_cvt_pk_bf16_f32 v24, v30, v31
	v_cvt_pk_bf16_f32 v25, v28, v29
	v_cvt_pk_bf16_f32 v26, v26, v27
	v_cvt_pk_bf16_f32 v27, v32, v33
	flat_store_dwordx4 v[88:89], v[24:27] offset:256

; __device__ __forceinline__ unsigned cvt_pk_bf16(float lo, float hi) { unsigned r; asm volatile("v_cvt_pk_bf16_f32 %0, %1, %2" : "=v"(r) : "v"(lo), "v"(hi)); return r; }
;     __device__ __forceinline__ void fused(f32x4 (&acc)[2][2][4][2], const Unit& u, int wr, int wc, int fr, int fq, PG8_LAS unsigned char* lds, int wid, int lane) const {
;     ...
;             for (int n = 0; n < 2; ++n) { sh[n] = (f32x4){0.f, 0.f, 0.f, 0.f}; sg[n] = sh[n];
;                 if (HH) { sh[n] = *(const f32x4*)(shift + (size_t)b * 9216 + c + 4 * n); sg[n] = (*(const f32x4*)(shift + (size_t)b * 9216 + 1024 + c + 4 * n) + 1.0f) * *(const f32x4*)(gpre + c + 4 * n); } }
; #pragma unroll
;             for (int ai = 0; ai < 2; ++ai)
; #pragma unroll
;                 for (int m = 0; m < 4; ++m) { const int r = ai * HALF + wr * 64 + m * 16 + fr; const size_t off = (size_t)(u.pm * BM + r) * 1024 + c;
;                     const f32x4 x0 = acc[ai][bj][m][0], x1 = acc[ai][bj][m][1];
;                     if (XF) { *(f32x4*)(XF + off) = x0; *(f32x4*)(XF + off + 4) = x1; }
;                     else { u32x4v w; w.x = cvt_pk_f16(x0[0], x0[1]); w.y = cvt_pk_f16(x0[2], x0[3]); w.z = cvt_pk_f16(x1[0], x1[1]); w.w = cvt_pk_f16(x1[2], x1[3]); *(u32x4v*)(X + off) = w; }
;                     if (HH) { const float rs = S[r]; const f32x4 o0 = x0 * rs * sg[0] + sh[0], o1 = x1 * rs * sg[1] + sh[1];
;                         u32x4v w; w.x = cvt_pk_bf16(o0[0], o0[1]); w.y = cvt_pk_bf16(o0[2], o0[3]); w.z = cvt_pk_bf16(o1[0], o1[1]); w.w = cvt_pk_bf16(o1[2], o1[3]); *(u32x4v*)(HH + off) = w; } }
.LBB0_849:
	s_and_b64 vcc, exec, s[0:1]
	s_cbranch_vccnz .LBB0_851
	s_waitcnt lgkmcnt(0)
	v_mov_b32_e32 v24, v247
	s_waitcnt lgkmcnt(0)
	v_pk_mul_f32 v[28:29], v[58:59], v[24:25] op_sel_hi:[1,0]
	v_pk_mul_f32 v[20:21], v[20:21], v[24:25] op_sel_hi:[1,0]
	v_pk_mul_f32 v[22:23], v[22:23], v[24:25] op_sel_hi:[1,0]
	v_pk_mul_f32 v[26:27], v[56:57], v[24:25] op_sel_hi:[1,0]
	v_pk_fma_f32 v[24:25], v[100:101], v[28:29], v[66:67]
	v_pk_fma_f32 v[28:29], v[104:105], v[22:23], v[54:55]
	v_pk_fma_f32 v[22:23], v[102:103], v[20:21], v[52:53]
	v_pk_fma_f32 v[26:27], v[0:1], v[26:27], v[64:65]
	s_nop 0
	v_cvt_pk_bf16_f32 v20, v26, v27
	v_cvt_pk_bf16_f32 v21, v24, v25
	v_cvt_pk_bf16_f32 v22, v22, v23
	v_cvt_pk_bf16_f32 v23, v28, v29
	flat_store_dwordx4 v[90:91], v[20:23] offset:256

; __device__ __forceinline__ unsigned cvt_pk_bf16(float lo, float hi) { unsigned r; asm volatile("v_cvt_pk_bf16_f32 %0, %1, %2" : "=v"(r) : "v"(lo), "v"(hi)); return r; }
;     __device__ __forceinline__ void fused(f32x4 (&acc)[2][2][4][2], const Unit& u, int wr, int wc, int fr, int fq, PG8_LAS unsigned char* lds, int wid, int lane) const {
;     ...
;             for (int n = 0; n < 2; ++n) { sh[n] = (f32x4){0.f, 0.f, 0.f, 0.f}; sg[n] = sh[n];
;                 if (HH) { sh[n] = *(const f32x4*)(shift + (size_t)b * 9216 + c + 4 * n); sg[n] = (*(const f32x4*)(shift + (size_t)b * 9216 + 1024 + c + 4 * n) + 1.0f) * *(const f32x4*)(gpre + c + 4 * n); } }
; #pragma unroll
;             for (int ai = 0; ai < 2; ++ai)
; #pragma unroll
;                 for (int m = 0; m < 4; ++m) { const int r = ai * HALF + wr * 64 + m * 16 + fr; const size_t off = (size_t)(u.pm * BM + r) * 1024 + c;
;                     const f32x4 x0 = acc[ai][bj][m][0], x1 = acc[ai][bj][m][1];
;                     if (XF) { *(f32x4*)(XF + off) = x0; *(f32x4*)(XF + off + 4) = x1; }
;                     else { u32x4v w; w.x = cvt_pk_f16(x0[0], x0[1]); w.y = cvt_pk_f16(x0[2], x0[3]); w.z = cvt_pk_f16(x1[0], x1[1]); w.w = cvt_pk_f16(x1[2], x1[3]); *(u32x4v*)(X + off) = w; }
;                     if (HH) { const float rs = S[r]; const f32x4 o0 = x0 * rs * sg[0] + sh[0], o1 = x1 * rs * sg[1] + sh[1];
;                         u32x4v w; w.x = cvt_pk_bf16(o0[0], o0[1]); w.y = cvt_pk_bf16(o0[2], o0[3]); w.z = cvt_pk_bf16(o1[0], o1[1]); w.w = cvt_pk_bf16(o1[2], o1[3]); *(u32x4v*)(HH + off) = w; } }
.LBB0_854:
	s_and_b64 vcc, exec, s[0:1]
	s_cbranch_vccnz .LBB0_856
	s_waitcnt lgkmcnt(0)
	v_mov_b32_e32 v20, v248
	s_waitcnt lgkmcnt(0)
	v_pk_mul_f32 v[24:25], v[50:51], v[20:21] op_sel_hi:[1,0]
	v_pk_mul_f32 v[16:17], v[16:17], v[20:21] op_sel_hi:[1,0]
	v_pk_mul_f32 v[18:19], v[18:19], v[20:21] op_sel_hi:[1,0]
	v_pk_mul_f32 v[22:23], v[48:49], v[20:21] op_sel_hi:[1,0]
	v_pk_fma_f32 v[20:21], v[100:101], v[24:25], v[66:67]
	v_pk_fma_f32 v[24:25], v[104:105], v[18:19], v[54:55]
	v_pk_fma_f32 v[18:19], v[102:103], v[16:17], v[52:53]
	v_pk_fma_f32 v[22:23], v[0:1], v[22:23], v[64:65]
	s_nop 0
	v_cvt_pk_bf16_f32 v16, v22, v23
	v_cvt_pk_bf16_f32 v17, v20, v21
	v_cvt_pk_bf16_f32 v18, v18, v19
	v_cvt_pk_bf16_f32 v19, v24, v25
	flat_store_dwordx4 v[72:73], v[16:19] offset:256

; __device__ __forceinline__ unsigned cvt_pk_bf16(float lo, float hi) { unsigned r; asm volatile("v_cvt_pk_bf16_f32 %0, %1, %2" : "=v"(r) : "v"(lo), "v"(hi)); return r; }
;     __device__ __forceinline__ void fused(f32x4 (&acc)[2][2][4][2], const Unit& u, int wr, int wc, int fr, int fq, PG8_LAS unsigned char* lds, int wid, int lane) const {
;     ...
;             for (int n = 0; n < 2; ++n) { sh[n] = (f32x4){0.f, 0.f, 0.f, 0.f}; sg[n] = sh[n];
;                 if (HH) { sh[n] = *(const f32x4*)(shift + (size_t)b * 9216 + c + 4 * n); sg[n] = (*(const f32x4*)(shift + (size_t)b * 9216 + 1024 + c + 4 * n) + 1.0f) * *(const f32x4*)(gpre + c + 4 * n); } }
; #pragma unroll
;             for (int ai = 0; ai < 2; ++ai)
; #pragma unroll
;                 for (int m = 0; m < 4; ++m) { const int r = ai * HALF + wr * 64 + m * 16 + fr; const size_t off = (size_t)(u.pm * BM + r) * 1024 + c;
;                     const f32x4 x0 = acc[ai][bj][m][0], x1 = acc[ai][bj][m][1];
;                     if (XF) { *(f32x4*)(XF + off) = x0; *(f32x4*)(XF + off + 4) = x1; }
;                     else { u32x4v w; w.x = cvt_pk_f16(x0[0], x0[1]); w.y = cvt_pk_f16(x0[2], x0[3]); w.z = cvt_pk_f16(x1[0], x1[1]); w.w = cvt_pk_f16(x1[2], x1[3]); *(u32x4v*)(X + off) = w; }
;                     if (HH) { const float rs = S[r]; const f32x4 o0 = x0 * rs * sg[0] + sh[0], o1 = x1 * rs * sg[1] + sh[1];
;                         u32x4v w; w.x = cvt_pk_bf16(o0[0], o0[1]); w.y = cvt_pk_bf16(o0[2], o0[3]); w.z = cvt_pk_bf16(o1[0], o1[1]); w.w = cvt_pk_bf16(o1[2], o1[3]); *(u32x4v*)(HH + off) = w; } }
.LBB0_859:
	s_and_b64 vcc, exec, s[0:1]
	s_cbranch_vccnz .LBB0_861
	s_waitcnt lgkmcnt(0)
	v_mov_b32_e32 v16, v249
	s_waitcnt lgkmcnt(0)
	v_pk_mul_f32 v[20:21], v[46:47], v[16:17] op_sel_hi:[1,0]
	v_pk_mul_f32 v[12:13], v[12:13], v[16:17] op_sel_hi:[1,0]
	v_pk_mul_f32 v[14:15], v[14:15], v[16:17] op_sel_hi:[1,0]
	v_pk_mul_f32 v[18:19], v[44:45], v[16:17] op_sel_hi:[1,0]
	v_pk_fma_f32 v[16:17], v[100:101], v[20:21], v[66:67]
	v_pk_fma_f32 v[20:21], v[104:105], v[14:15], v[54:55]
	v_pk_fma_f32 v[14:15], v[102:103], v[12:13], v[52:53]
	v_pk_fma_f32 v[18:19], v[0:1], v[18:19], v[64:65]
	s_nop 0
	v_cvt_pk_bf16_f32 v12, v18, v19
	v_cvt_pk_bf16_f32 v13, v16, v17
	v_cvt_pk_bf16_f32 v14, v14, v15
	v_cvt_pk_bf16_f32 v15, v20, v21
	flat_store_dwordx4 v[74:75], v[12:15] offset:256

; __device__ __forceinline__ unsigned cvt_pk_bf16(float lo, float hi) { unsigned r; asm volatile("v_cvt_pk_bf16_f32 %0, %1, %2" : "=v"(r) : "v"(lo), "v"(hi)); return r; }
;     __device__ __forceinline__ void fused(f32x4 (&acc)[2][2][4][2], const Unit& u, int wr, int wc, int fr, int fq, PG8_LAS unsigned char* lds, int wid, int lane) const {
;     ...
;             for (int n = 0; n < 2; ++n) { sh[n] = (f32x4){0.f, 0.f, 0.f, 0.f}; sg[n] = sh[n];
;                 if (HH) { sh[n] = *(const f32x4*)(shift + (size_t)b * 9216 + c + 4 * n); sg[n] = (*(const f32x4*)(shift + (size_t)b * 9216 + 1024 + c + 4 * n) + 1.0f) * *(const f32x4*)(gpre + c + 4 * n); } }
; #pragma unroll
;             for (int ai = 0; ai < 2; ++ai)
; #pragma unroll
;                 for (int m = 0; m < 4; ++m) { const int r = ai * HALF + wr * 64 + m * 16 + fr; const size_t off = (size_t)(u.pm * BM + r) * 1024 + c;
;                     const f32x4 x0 = acc[ai][bj][m][0], x1 = acc[ai][bj][m][1];
;                     if (XF) { *(f32x4*)(XF + off) = x0; *(f32x4*)(XF + off + 4) = x1; }
;                     else { u32x4v w; w.x = cvt_pk_f16(x0[0], x0[1]); w.y = cvt_pk_f16(x0[2], x0[3]); w.z = cvt_pk_f16(x1[0], x1[1]); w.w = cvt_pk_f16(x1[2], x1[3]); *(u32x4v*)(X + off) = w; }
;                     if (HH) { const float rs = S[r]; const f32x4 o0 = x0 * rs * sg[0] + sh[0], o1 = x1 * rs * sg[1] + sh[1];
;                         u32x4v w; w.x = cvt_pk_bf16(o0[0], o0[1]); w.y = cvt_pk_bf16(o0[2], o0[3]); w.z = cvt_pk_bf16(o1[0], o1[1]); w.w = cvt_pk_bf16(o1[2], o1[3]); *(u32x4v*)(HH + off) = w; } }
.LBB0_864:
	s_and_b64 vcc, exec, s[0:1]
	s_cbranch_vccnz .LBB0_866
	s_waitcnt lgkmcnt(0)
	v_mov_b32_e32 v12, v250
	s_waitcnt lgkmcnt(0)
	v_pk_mul_f32 v[16:17], v[42:43], v[12:13] op_sel_hi:[1,0]
	v_pk_mul_f32 v[8:9], v[8:9], v[12:13] op_sel_hi:[1,0]
	v_pk_mul_f32 v[10:11], v[10:11], v[12:13] op_sel_hi:[1,0]
	v_pk_mul_f32 v[14:15], v[40:41], v[12:13] op_sel_hi:[1,0]
	v_pk_fma_f32 v[12:13], v[100:101], v[16:17], v[66:67]
	v_pk_fma_f32 v[16:17], v[104:105], v[10:11], v[54:55]
	v_pk_fma_f32 v[10:11], v[102:103], v[8:9], v[52:53]
	v_pk_fma_f32 v[14:15], v[0:1], v[14:15], v[64:65]
	s_nop 0
	v_cvt_pk_bf16_f32 v8, v14, v15
	v_cvt_pk_bf16_f32 v9, v12, v13
	v_cvt_pk_bf16_f32 v10, v10, v11
	v_cvt_pk_bf16_f32 v11, v16, v17
	flat_store_dwordx4 v[80:81], v[8:11] offset:256

; __device__ __forceinline__ unsigned cvt_pk_bf16(float lo, float hi) { unsigned r; asm volatile("v_cvt_pk_bf16_f32 %0, %1, %2" : "=v"(r) : "v"(lo), "v"(hi)); return r; }
;     __device__ __forceinline__ void fused(f32x4 (&acc)[2][2][4][2], const Unit& u, int wr, int wc, int fr, int fq, PG8_LAS unsigned char* lds, int wid, int lane) const {
;     ...
;             for (int n = 0; n < 2; ++n) { sh[n] = (f32x4){0.f, 0.f, 0.f, 0.f}; sg[n] = sh[n];
;                 if (HH) { sh[n] = *(const f32x4*)(shift + (size_t)b * 9216 + c + 4 * n); sg[n] = (*(const f32x4*)(shift + (size_t)b * 9216 + 1024 + c + 4 * n) + 1.0f) * *(const f32x4*)(gpre + c + 4 * n); } }
; #pragma unroll
;             for (int ai = 0; ai < 2; ++ai)
; #pragma unroll
;                 for (int m = 0; m < 4; ++m) { const int r = ai * HALF + wr * 64 + m * 16 + fr; const size_t off = (size_t)(u.pm * BM + r) * 1024 + c;
;                     const f32x4 x0 = acc[ai][bj][m][0], x1 = acc[ai][bj][m][1];
;                     if (XF) { *(f32x4*)(XF + off) = x0; *(f32x4*)(XF + off + 4) = x1; }
;                     else { u32x4v w; w.x = cvt_pk_f16(x0[0], x0[1]); w.y = cvt_pk_f16(x0[2], x0[3]); w.z = cvt_pk_f16(x1[0], x1[1]); w.w = cvt_pk_f16(x1[2], x1[3]); *(u32x4v*)(X + off) = w; }
;                     if (HH) { const float rs = S[r]; const f32x4 o0 = x0 * rs * sg[0] + sh[0], o1 = x1 * rs * sg[1] + sh[1];
;                         u32x4v w; w.x = cvt_pk_bf16(o0[0], o0[1]); w.y = cvt_pk_bf16(o0[2], o0[3]); w.z = cvt_pk_bf16(o1[0], o1[1]); w.w = cvt_pk_bf16(o1[2], o1[3]); *(u32x4v*)(HH + off) = w; } }
.LBB0_869:
	s_and_b64 vcc, exec, s[0:1]
	s_cbranch_vccnz .LBB0_871
	s_waitcnt lgkmcnt(0)
	v_mov_b32_e32 v2, v251
	s_waitcnt lgkmcnt(0)
	v_pk_mul_f32 v[8:9], v[36:37], v[2:3] op_sel_hi:[1,0]
	v_pk_mul_f32 v[4:5], v[4:5], v[2:3] op_sel_hi:[1,0]
	v_pk_mul_f32 v[6:7], v[6:7], v[2:3] op_sel_hi:[1,0]
	v_pk_mul_f32 v[10:11], v[38:39], v[2:3] op_sel_hi:[1,0]
	v_pk_fma_f32 v[0:1], v[0:1], v[8:9], v[64:65]
	v_pk_fma_f32 v[8:9], v[104:105], v[6:7], v[54:55]
	v_pk_fma_f32 v[6:7], v[102:103], v[4:5], v[52:53]
	v_pk_fma_f32 v[10:11], v[100:101], v[10:11], v[66:67]
	v_cvt_pk_bf16_f32 v4, v0, v1
	s_nop 0
	v_cvt_pk_bf16_f32 v5, v10, v11
	v_cvt_pk_bf16_f32 v6, v6, v7
	v_cvt_pk_bf16_f32 v7, v8, v9
	flat_store_dwordx4 v[68:69], v[4:7] offset:256
